# P0 row loop software-pipelined by hand: next trip's eight x loads requested right after the current values are copied out of prefetch registers
# baseline (speedup 1.0000x reference)
.LBB0_16:
	v_writelane_b32 v254, s12, 4
	s_nop 1
	v_writelane_b32 v254, s13, 5
	v_writelane_b32 v254, s14, 6
	v_writelane_b32 v254, s15, 7
	v_writelane_b32 v254, s16, 8
	v_writelane_b32 v254, s17, 9
	v_writelane_b32 v254, s18, 10
	v_writelane_b32 v254, s19, 11
	v_writelane_b32 v254, s20, 12
	v_writelane_b32 v254, s21, 13
	v_writelane_b32 v254, s22, 14
	v_writelane_b32 v254, s23, 15
	v_writelane_b32 v254, s24, 16
	v_writelane_b32 v254, s25, 17
	v_writelane_b32 v254, s26, 18
	v_writelane_b32 v254, s27, 19
	s_or_b64 exec, exec, s[0:1]
	s_load_dwordx16 s[64:79], s[80:81], 0x0
	s_load_dwordx16 s[40:55], s[80:81], 0x80
	v_lshrrev_b32_e32 v1, 6, v0
	v_lshl_or_b32 v198, s59, 3, v1
	s_movk_i32 s26, 0x4100
	v_cmp_gt_i32_e32 vcc, s26, v198
	v_mbcnt_lo_u32_b32 v1, -1, 0
	s_waitcnt lgkmcnt(0)
	s_barrier
	s_and_saveexec_b64 s[0:1], vcc
	s_cbranch_execz .LBB0_55
	v_mbcnt_hi_u32_b32 v22, -1, v1
	v_and_b32_e32 v10, 64, v22
	v_add_u32_e32 v23, 64, v10
	v_xor_b32_e32 v10, 32, v22
	v_cmp_lt_i32_e32 vcc, v10, v23
	s_load_dwordx16 s[8:23], s[80:81], 0x40
	v_and_b32_e32 v21, 63, v0
	v_cndmask_b32_e32 v10, v22, v10, vcc
	v_lshlrev_b32_e32 v90, 2, v10
	v_xor_b32_e32 v10, 16, v22
	v_cmp_lt_i32_e32 vcc, v10, v23
	v_lshlrev_b32_e32 v24, 4, v21
	s_waitcnt lgkmcnt(0)
	global_load_dwordx4 v[2:5], v24, s[8:9]
	global_load_dwordx4 v[6:9], v24, s[8:9] offset:1024
	v_cndmask_b32_e32 v10, v22, v10, vcc
	v_lshlrev_b32_e32 v91, 2, v10
	v_xor_b32_e32 v10, 8, v22
	v_cmp_lt_i32_e32 vcc, v10, v23
	v_xor_b32_e32 v25, 4, v22
	v_mov_b32_e32 v47, 0
	v_cndmask_b32_e32 v10, v22, v10, vcc
	v_lshlrev_b32_e32 v92, 2, v10
	global_load_dwordx4 v[10:13], v24, s[8:9] offset:2048
	global_load_dwordx4 v[14:17], v24, s[8:9] offset:3072
	v_cmp_lt_i32_e32 vcc, v25, v23
	v_lshlrev_b32_e32 v46, 3, v21
	s_mov_b64 s[2:3], 0x1e6ea00
	v_cndmask_b32_e32 v25, v22, v25, vcc
	v_lshlrev_b32_e32 v93, 2, v25
	v_xor_b32_e32 v25, 2, v22
	v_cmp_lt_i32_e32 vcc, v25, v23
	v_add_u32_e32 v96, 16, v24
	v_mov_b32_e32 v53, v47
	v_cndmask_b32_e32 v25, v22, v25, vcc
	v_lshlrev_b32_e32 v94, 2, v25
	v_xor_b32_e32 v25, 1, v22
	v_cmp_lt_i32_e32 vcc, v25, v23
	s_mov_b64 s[14:15], 0x1880000
	v_ashrrev_i32_e32 v199, 31, v198
	v_cndmask_b32_e32 v22, v22, v25, vcc
	v_lshlrev_b32_e32 v95, 2, v22
	v_lshl_add_u64 v[22:23], s[90:91], 0, v[46:47]
	v_lshl_add_u64 v[50:51], v[22:23], 0, s[2:3]
	v_bfe_u32 v22, v0, 2, 4
	v_subrev_co_u32_e32 v52, vcc, 8, v22
	v_lshlrev_b32_e32 v22, 2, v22
	v_mov_b32_e32 v23, v47
	v_lshl_add_u64 v[24:25], s[90:91], 0, v[22:23]
	v_lshlrev_b32_e32 v20, 2, v21
	v_lshlrev_b32_e32 v48, 3, v19
	v_cmp_gt_u32_e64 s[2:3], 32, v21
	v_and_b32_e32 v21, 16, v0
	v_cmp_eq_u32_e64 s[12:13], 0, v18
	v_lshl_add_u64 v[54:55], v[24:25], 0, s[14:15]
	v_lshlrev_b32_e32 v56, 4, v19
	v_lshlrev_b64 v[18:19], 2, v[52:53]
	v_lshlrev_b64 v[24:25], 5, v[198:199]
	v_cmp_eq_u32_e64 s[6:7], 0, v21
	v_and_b32_e32 v21, 8, v0
	v_lshl_add_u64 v[58:59], s[40:41], 0, v[18:19]
	v_lshl_add_u64 v[60:61], s[16:17], 0, v[22:23]
	v_lshl_add_u64 v[22:23], v[24:25], 0, v[22:23]
	v_lshl_add_u64 v[18:19], v[24:25], 0, v[18:19]
	v_cmp_eq_u32_e64 s[8:9], 0, v21
	v_and_b32_e32 v21, 4, v0
	v_ashrrev_i32_e32 v57, 31, v56
	v_lshl_add_u64 v[62:63], v[22:23], 0, s[14:15]
	v_lshl_add_u64 v[18:19], s[88:89], 0, v[18:19]
	s_mov_b64 s[14:15], 0x8100000
	v_lshlrev_b64 v[68:69], 11, v[198:199]
	v_add_u32_e32 v97, 0x8000, v96
	v_cmp_eq_u32_e64 s[10:11], 0, v21
	s_xor_b64 s[4:5], vcc, -1
	v_lshlrev_b64 v[64:65], 5, v[56:57]
	v_lshl_add_u64 v[66:67], v[18:19], 0, s[14:15]
	v_or_b32_e32 v68, v68, v46
	v_lshlrev_b64 v[70:71], 11, v[56:57]
	v_mov_b32_e32 v49, v47
	s_mov_b64 s[18:19], 0
	s_movk_i32 s27, 0x40ff
	s_movk_i32 s28, 0x3fff
	s_movk_i32 s29, 0x4000
	v_lshlrev_b32_e32 v72, 2, v20
	v_mov_b32_e32 v98, 0x358637bd
	s_mov_b32 s30, 0x800000
	s_mov_b32 s31, 0xc1a00000
	s_mov_b32 s33, 0xbfb8aa3b
	s_mov_b32 s34, 0x42ce8ed0
	s_mov_b32 s35, 0xc2b17218
	s_mov_b32 s36, 0x7f800000
	s_mov_b32 s37, 0x3f2aaaab
	v_mov_b32_e32 v99, 0x3ecc95a3
	s_mov_b32 s38, 0x3f317218
	s_mov_b32 s39, 0x33800000
	s_mov_b32 s40, 0x41a00000
	s_mov_b32 s41, 0x3fb8aa3b
	s_mov_b32 s56, 0xc2ce8ed0
	s_mov_b32 s57, 0x42b17218
	v_mov_b32_e32 v100, 0x7f800000
	v_mov_b32_e32 v74, 0x3f317218
	v_mov_b64_e32 v[76:77], v[198:199]
	v_mov_b32_e32 v164, v76
	v_mov_b32_e32 v174, v72
	v_mov_b32_e32 v175, 0
	v_add_u32_e32 v165, v164, v48
	v_cmp_gt_i32_e64 s[84:85], s26, v165
	v_mov_b32_e32 v171, 0
	v_mov_b32_e32 v177, 0
	v_cndmask_b32_e64 v165, v164, v165, s[84:85]
	v_cmp_gt_i32_e32 vcc, s29, v164
	v_add_u32_e32 v170, 0xffffc000, v164
	v_mov_b32_e32 v172, s66
	v_mov_b32_e32 v173, s67
	v_cndmask_b32_e32 v170, v170, v164, vcc
	v_mov_b32_e32 v166, s64
	v_mov_b32_e32 v167, s65
	v_cndmask_b32_e32 v172, v172, v166, vcc
	v_cndmask_b32_e32 v173, v173, v167, vcc
	v_lshlrev_b64 v[170:171], 12, v[170:171]
	v_lshl_add_u64 v[166:167], v[172:173], 0, v[170:171]
	v_lshl_add_u64 v[166:167], v[166:167], 0, v[174:175]
	v_cmp_gt_i32_e32 vcc, s29, v165
	v_add_u32_e32 v176, 0xffffc000, v165
	v_mov_b32_e32 v172, s66
	v_mov_b32_e32 v173, s67
	v_cndmask_b32_e32 v176, v176, v165, vcc
	v_mov_b32_e32 v168, s64
	v_mov_b32_e32 v169, s65
	v_cndmask_b32_e32 v172, v172, v168, vcc
	v_cndmask_b32_e32 v173, v173, v169, vcc
	v_lshlrev_b64 v[176:177], 12, v[176:177]
	v_lshl_add_u64 v[168:169], v[172:173], 0, v[176:177]
	v_lshl_add_u64 v[168:169], v[168:169], 0, v[174:175]
	global_load_dwordx4 v[132:135], v[166:167], off
	global_load_dwordx4 v[136:139], v[166:167], off offset:1024
	global_load_dwordx4 v[140:143], v[166:167], off offset:2048
	global_load_dwordx4 v[144:147], v[166:167], off offset:3072
	global_load_dwordx4 v[148:151], v[168:169], off
	global_load_dwordx4 v[152:155], v[168:169], off offset:1024
	global_load_dwordx4 v[156:159], v[168:169], off offset:2048
	global_load_dwordx4 v[160:163], v[168:169], off offset:3072
	s_waitcnt vmcnt(0)
	s_branch .LBB0_20

.LBB0_20:
	v_add_u32_e32 v46, 0xffffc000, v76
	v_cmp_gt_i32_e32 vcc, s29, v76
	v_mov_b32_e32 v36, s67
	v_mov_b32_e32 v37, s65
	s_waitcnt lgkmcnt(0)
	v_cndmask_b32_e32 v19, 0, v77, vcc
	v_cndmask_b32_e32 v18, v46, v76, vcc
	v_mov_b32_e32 v38, s66
	v_mov_b32_e32 v39, s64
	v_cndmask_b32_e32 v21, v36, v37, vcc
	v_cndmask_b32_e32 v20, v38, v39, vcc
	v_lshlrev_b64 v[18:19], 12, v[18:19]
	v_lshl_add_u64 v[18:19], v[20:21], 0, v[18:19]
	v_mov_b32_e32 v73, v47
	v_lshl_add_u64 v[26:27], v[18:19], 0, v[72:73]
	s_waitcnt vmcnt(4)
	v_mov_b32_e32 v22, v132
	v_mov_b32_e32 v23, v133
	v_mov_b32_e32 v24, v134
	v_mov_b32_e32 v25, v135
	v_mov_b32_e32 v18, v136
	v_mov_b32_e32 v19, v137
	v_mov_b32_e32 v20, v138
	v_mov_b32_e32 v21, v139
	v_mov_b32_e32 v30, v140
	v_mov_b32_e32 v31, v141
	v_mov_b32_e32 v32, v142
	v_mov_b32_e32 v33, v143
	s_nop 0
	v_mov_b32_e32 v26, v144
	v_mov_b32_e32 v27, v145
	v_mov_b32_e32 v28, v146
	v_mov_b32_e32 v29, v147
	v_lshl_add_u64 v[78:79], v[48:49], 0, v[76:77]
	v_cmp_gt_i32_e64 s[14:15], s26, v78
	s_mov_b32 s16, 0x1e6e000
	v_mov_b32_e32 v86, v23
	v_cndmask_b32_e64 v34, 0, v48, s[14:15]
	v_add_u32_e32 v40, v76, v34
	v_ashrrev_i32_e32 v35, 31, v34
	v_lshl_add_u64 v[34:35], v[76:77], 0, v[34:35]
	v_add_u32_e32 v41, 0xffffc000, v40
	v_cmp_gt_i32_e32 vcc, s29, v40
	v_mov_b32_e32 v87, v19
	v_mov_b32_e32 v84, v22
	v_cndmask_b32_e32 v35, 0, v35, vcc
	v_cndmask_b32_e32 v34, v41, v34, vcc
	v_cndmask_b32_e32 v37, v36, v37, vcc
	v_cndmask_b32_e32 v36, v38, v39, vcc
	v_lshlrev_b64 v[34:35], 12, v[34:35]
	v_lshl_add_u64 v[34:35], v[36:37], 0, v[34:35]
	v_lshl_add_u64 v[34:35], v[34:35], 0, v[72:73]
	v_mov_b32_e32 v80, v148
	v_mov_b32_e32 v81, v149
	v_mov_b32_e32 v82, v150
	v_mov_b32_e32 v83, v151
	v_mov_b32_e32 v42, v152
	v_mov_b32_e32 v43, v153
	v_mov_b32_e32 v44, v154
	v_mov_b32_e32 v45, v155
	v_mov_b32_e32 v38, v156
	v_mov_b32_e32 v39, v157
	v_mov_b32_e32 v40, v158
	v_mov_b32_e32 v41, v159
	s_nop 0
	v_mov_b32_e32 v34, v160
	v_mov_b32_e32 v35, v161
	v_mov_b32_e32 v36, v162
	v_mov_b32_e32 v37, v163
	v_add_u32_e32 v164, v76, v56
	v_cmp_gt_i32_e64 s[82:83], s26, v164
	v_mov_b32_e32 v174, v72
	v_mov_b32_e32 v175, 0
	v_cndmask_b32_e64 v164, v76, v164, s[82:83]
	v_add_u32_e32 v165, v164, v48
	v_cmp_gt_i32_e64 s[84:85], s26, v165
	v_mov_b32_e32 v171, 0
	v_mov_b32_e32 v177, 0
	v_cndmask_b32_e64 v165, v164, v165, s[84:85]
	v_cmp_gt_i32_e32 vcc, s29, v164
	v_add_u32_e32 v170, 0xffffc000, v164
	v_mov_b32_e32 v172, s66
	v_mov_b32_e32 v173, s67
	v_cndmask_b32_e32 v170, v170, v164, vcc
	v_mov_b32_e32 v166, s64
	v_mov_b32_e32 v167, s65
	v_cndmask_b32_e32 v172, v172, v166, vcc
	v_cndmask_b32_e32 v173, v173, v167, vcc
	v_lshlrev_b64 v[170:171], 12, v[170:171]
	v_lshl_add_u64 v[166:167], v[172:173], 0, v[170:171]
	v_lshl_add_u64 v[166:167], v[166:167], 0, v[174:175]
	v_cmp_gt_i32_e32 vcc, s29, v165
	v_add_u32_e32 v176, 0xffffc000, v165
	v_mov_b32_e32 v172, s66
	v_mov_b32_e32 v173, s67
	v_cndmask_b32_e32 v176, v176, v165, vcc
	v_mov_b32_e32 v168, s64
	v_mov_b32_e32 v169, s65
	v_cndmask_b32_e32 v172, v172, v168, vcc
	v_cndmask_b32_e32 v173, v173, v169, vcc
	v_lshlrev_b64 v[176:177], 12, v[176:177]
	v_lshl_add_u64 v[168:169], v[172:173], 0, v[176:177]
	v_lshl_add_u64 v[168:169], v[168:169], 0, v[174:175]
	global_load_dwordx4 v[132:135], v[166:167], off
	global_load_dwordx4 v[136:139], v[166:167], off offset:1024
	global_load_dwordx4 v[140:143], v[166:167], off offset:2048
	global_load_dwordx4 v[144:147], v[166:167], off offset:3072
	global_load_dwordx4 v[148:151], v[168:169], off
	global_load_dwordx4 v[152:155], v[168:169], off offset:1024
	global_load_dwordx4 v[156:159], v[168:169], off offset:2048
	global_load_dwordx4 v[160:163], v[168:169], off offset:3072
	v_mov_b32_e32 v85, v18
	v_mov_b32_e32 v102, v31
	v_mov_b32_e32 v103, v27
	v_pk_mul_f32 v[86:87], v[86:87], v[86:87]
	v_mov_b32_e32 v88, v30
	v_mov_b32_e32 v89, v26
	v_mov_b32_e32 v104, v24
	v_mov_b32_e32 v105, v20
	v_pk_mul_f32 v[102:103], v[102:103], v[102:103]
	v_pk_fma_f32 v[84:85], v[84:85], v[84:85], v[86:87]
	v_mov_b32_e32 v106, v32
	v_mov_b32_e32 v107, v28
	v_mov_b32_e32 v108, v25
	v_mov_b32_e32 v109, v21
	v_pk_fma_f32 v[86:87], v[88:89], v[88:89], v[102:103]
	v_pk_fma_f32 v[84:85], v[104:105], v[104:105], v[84:85]
	v_mov_b32_e32 v110, v33
	v_mov_b32_e32 v111, v29
	v_pk_fma_f32 v[86:87], v[106:107], v[106:107], v[86:87]
	v_pk_fma_f32 v[84:85], v[108:109], v[108:109], v[84:85]
	v_pk_fma_f32 v[86:87], v[110:111], v[110:111], v[86:87]
	v_add_f32_e32 v73, v84, v85
	v_add_f32_e32 v73, v73, v86
	v_add_f32_e32 v73, v73, v87
	ds_bpermute_b32 v75, v90, v73
	s_waitcnt lgkmcnt(0)
	v_add_f32_e32 v73, v73, v75
	ds_bpermute_b32 v75, v91, v73
	s_waitcnt lgkmcnt(0)
	v_add_f32_e32 v73, v73, v75
	ds_bpermute_b32 v75, v92, v73
	s_waitcnt lgkmcnt(0)
	v_add_f32_e32 v73, v73, v75
	ds_bpermute_b32 v75, v93, v73
	s_waitcnt lgkmcnt(0)
	v_add_f32_e32 v73, v73, v75
	ds_bpermute_b32 v75, v94, v73
	s_waitcnt lgkmcnt(0)
	v_add_f32_e32 v73, v73, v75
	ds_bpermute_b32 v75, v95, v73
	s_waitcnt lgkmcnt(0)
	v_add_f32_e32 v73, v73, v75
	v_fmamk_f32 v73, v73, 0x3a800000, v98
	v_mul_f32_e32 v75, 0x4b800000, v73
	v_cmp_gt_f32_e32 vcc, s30, v73
	v_mov_b32_e32 v102, v81
	v_mov_b32_e32 v103, v43
	v_mov_b32_e32 v88, v80
	v_mov_b32_e32 v89, v42
	v_mov_b32_e32 v106, v39
	v_mov_b32_e32 v107, v35
	v_pk_mul_f32 v[84:85], v[102:103], v[102:103]
	v_mov_b32_e32 v104, v38
	v_mov_b32_e32 v105, v34
	v_mov_b32_e32 v112, v82
	v_mov_b32_e32 v113, v44
	v_pk_mul_f32 v[86:87], v[106:107], v[106:107]
	v_pk_fma_f32 v[84:85], v[88:89], v[88:89], v[84:85]
	v_mov_b32_e32 v114, v40
	v_mov_b32_e32 v115, v36
	v_mov_b32_e32 v116, v83
	v_mov_b32_e32 v117, v45
	v_pk_fma_f32 v[86:87], v[104:105], v[104:105], v[86:87]
	v_pk_fma_f32 v[84:85], v[112:113], v[112:113], v[84:85]
	v_mov_b32_e32 v118, v41
	v_mov_b32_e32 v119, v37
	v_pk_fma_f32 v[86:87], v[114:115], v[114:115], v[86:87]
	v_pk_fma_f32 v[84:85], v[116:117], v[116:117], v[84:85]
	v_pk_fma_f32 v[86:87], v[118:119], v[118:119], v[86:87]
	v_add_f32_e32 v79, v84, v85
	v_add_f32_e32 v79, v79, v86
	v_add_f32_e32 v79, v79, v87
	ds_bpermute_b32 v84, v90, v79
	v_cndmask_b32_e32 v73, v73, v75, vcc
	v_rsq_f32_e32 v73, v73
	s_waitcnt lgkmcnt(0)
	v_add_f32_e32 v79, v79, v84
	ds_bpermute_b32 v84, v91, v79
	s_waitcnt lgkmcnt(0)
	v_add_f32_e32 v79, v79, v84
	ds_bpermute_b32 v86, v92, v79
	v_lshl_add_u64 v[84:85], s[90:91], 0, v[68:69]
	s_waitcnt lgkmcnt(0)
	v_add_f32_e32 v79, v79, v86
	ds_bpermute_b32 v88, v93, v79
	v_add_co_u32_e64 v86, s[16:17], s16, v84
	s_waitcnt lgkmcnt(0)
	v_add_f32_e32 v75, v79, v88
	v_mul_f32_e32 v79, 0x45800000, v73
	v_cndmask_b32_e32 v88, v73, v79, vcc
	v_pk_mul_f32 v[22:23], v[22:23], v[88:89] op_sel_hi:[1,0]
	v_pk_mul_f32 v[24:25], v[24:25], v[88:89] op_sel_hi:[1,0]
	v_pk_mul_f32 v[18:19], v[18:19], v[88:89] op_sel_hi:[1,0]
	v_pk_mul_f32 v[20:21], v[20:21], v[88:89] op_sel_hi:[1,0]
	v_addc_co_u32_e64 v87, s[16:17], 0, v85, s[16:17]
	v_pk_mul_f32 v[102:103], v[30:31], v[88:89] op_sel_hi:[1,0]
	v_pk_mul_f32 v[104:105], v[32:33], v[88:89] op_sel_hi:[1,0]
	v_pk_mul_f32 v[106:107], v[26:27], v[88:89] op_sel_hi:[1,0]
	v_pk_mul_f32 v[88:89], v[28:29], v[88:89] op_sel_hi:[1,0]
	v_pk_mul_f32 v[30:31], v[4:5], v[24:25]
	v_pk_mul_f32 v[32:33], v[2:3], v[22:23]
	v_pk_mul_f32 v[26:27], v[8:9], v[20:21]
	v_pk_mul_f32 v[28:29], v[6:7], v[18:19]
	v_cvt_pk_bf16_f32 v20, v32, v33
	v_cvt_pk_bf16_f32 v21, v30, v31
	v_cvt_pk_bf16_f32 v23, v26, v27
	s_mov_b32 s16, 0x1e6f000
	v_cvt_pk_bf16_f32 v22, v28, v29
	global_store_dwordx2 v[86:87], v[20:21], off offset:2560
	global_store_dwordx2 v[86:87], v[22:23], off offset:3072
	ds_bpermute_b32 v22, v94, v75
	v_add_co_u32_e32 v84, vcc, s16, v84
	v_pk_mul_f32 v[18:19], v[12:13], v[104:105]
	s_nop 0
	v_addc_co_u32_e32 v85, vcc, 0, v85, vcc
	s_waitcnt lgkmcnt(0)
	v_add_f32_e32 v73, v75, v22
	ds_bpermute_b32 v75, v95, v73
	v_pk_mul_f32 v[24:25], v[10:11], v[102:103]
	v_cvt_pk_bf16_f32 v21, v18, v19
	v_pk_mul_f32 v[22:23], v[14:15], v[106:107]
	v_cvt_pk_bf16_f32 v20, v24, v25
	s_waitcnt lgkmcnt(0)
	v_add_f32_e32 v73, v73, v75
	v_fmamk_f32 v73, v73, 0x3a800000, v98
	v_mul_f32_e32 v75, 0x4b800000, v73
	v_cmp_gt_f32_e32 vcc, s30, v73
	global_store_dwordx2 v[86:87], v[20:21], off offset:3584
	v_cvt_pk_bf16_f32 v86, v22, v23
	v_pk_mul_f32 v[20:21], v[16:17], v[88:89]
	v_cndmask_b32_e32 v73, v73, v75, vcc
	v_rsq_f32_e32 v73, v73
	v_cvt_pk_bf16_f32 v87, v20, v21
	global_store_dwordx2 v[84:85], v[86:87], off
	v_ashrrev_i32_e32 v79, 31, v78
	v_mul_f32_e32 v75, 0x45800000, v73
	v_cndmask_b32_e32 v86, v73, v75, vcc
	v_pk_mul_f32 v[88:89], v[80:81], v[86:87] op_sel_hi:[1,0]
	v_pk_mul_f32 v[80:81], v[82:83], v[86:87] op_sel_hi:[1,0]
	v_lshlrev_b64 v[82:83], 11, v[78:79]
	v_cmp_lt_i32_e64 s[16:17], s27, v78
	v_cmp_lt_i32_e32 vcc, s28, v76
	v_lshl_add_u64 v[84:85], v[50:51], 0, v[82:83]
	v_pk_mul_f32 v[80:81], v[4:5], v[80:81]
	v_pk_mul_f32 v[82:83], v[2:3], v[88:89]
	s_and_saveexec_b64 s[20:21], s[14:15]
	s_cbranch_execz .LBB0_22
	v_cvt_pk_bf16_f32 v88, v82, v83
	v_cvt_pk_bf16_f32 v89, v80, v81
	global_store_dwordx2 v[84:85], v[88:89], off
